# NA window tiles: bias index via pre-scaled base + med3 (2 VALU instead of 4), -m0 folded into the LDS bias table (one VALU less per element)
# speedup vs baseline: 1.0436x; 1.0053x over previous
; template <int DQK, bool NA, bool SMAX, int LDV> ...
;     ...
;   if (NA) { for (int i = tid; i < 465; i += 512) rpbl[i] = rpb_g[i] * LOG2E; }
; DI void phase_attn(const Params& p, int l, bool last, char* smem) {
;     ...
;     m0_na = c_na * 64.f * c * d + e * LOG2E;
.LBB0_1054:
	s_or_b64 exec, exec, s[26:27]
	s_and_b64 s[4:5], exec, s[40:41]
	s_mov_b64 s[40:41], 0x800
	s_mov_b64 exec, s[4:5]
	s_cbranch_execz .LBB0_1057
	s_add_i32 s4, 0, 0xa000
	v_lshl_add_u32 v0, v4, 2, s4
	v_readlane_b32 s64, v249, 20
	v_readlane_b32 s4, v248, 26
	v_readlane_b32 s65, v249, 21
	s_add_u32 s4, s64, s4
	v_readlane_b32 s5, v248, 25
	v_ashrrev_i32_e32 v5, 31, v4
	s_addc_u32 s5, s65, s5
	v_add_u32_e32 v3, 0xfffffe00, v4
	s_movk_i32 s26, 0xffd0
	v_lshl_add_u64 v[4:5], v[4:5], 2, s[4:5]
	s_mov_b64 s[4:5], 0
	v_readlane_b32 s66, v249, 22
	v_readlane_b32 s67, v249, 23
	v_readlane_b32 s68, v249, 24
	v_readlane_b32 s69, v249, 25
	v_readlane_b32 s70, v249, 26
	v_readlane_b32 s71, v249, 27
	v_readlane_b32 s72, v249, 28
	v_readlane_b32 s73, v249, 29
	v_readlane_b32 s74, v249, 30
	v_readlane_b32 s75, v249, 31
	v_readlane_b32 s76, v249, 32
	v_readlane_b32 s77, v249, 33
	v_readlane_b32 s78, v249, 34
	v_readlane_b32 s79, v249, 35
	s_mov_b32 s101, 0x3fb8aa3b
.LBB0_1056:
	global_load_dword v6, v[4:5], off
	v_add_u32_e32 v3, 0x200, v3
	v_cmp_lt_i32_e32 vcc, s26, v3
	v_lshl_add_u64 v[4:5], v[4:5], 0, s[40:41]
	s_or_b64 s[4:5], vcc, s[4:5]
	s_waitcnt vmcnt(0)
	v_fma_f32 v6, v6, s101, -v153
	ds_write_b32 v0, v6
	v_add_u32_e32 v0, 0x800, v0
	s_andn2_b64 exec, exec, s[4:5]
	s_cbranch_execnz .LBB0_1056

; template <int DQK, bool NA, bool SMAX, int LDV> ...
;     ...
;         if (NA && it >= 4) {
;           const int kr = rs + (it - 4);
;           const int ql = w * 32 + qt * 16 + fr, qr = r0 + (ql >> 6), qc = ql & 63;
;           const int rst = min(max(qr - 4, 0), 24);
;           const bool rowok = (kr >= rst) && (kr < rst + 8);
;           const int cst = min(max(qc - 8, 0), 48);
;           const int base = (kr - qr + 7) * 31 + 15 - qc;
;           float bv[4][4];
; #pragma unroll
;           for (int kt = 0; kt < 4; ++kt)
; #pragma unroll
;             for (int j = 0; j < 4; ++j) bv[kt][j] = rpbl[min(max(base + kt * 16 + fq * 4 + j, 0), 464)];
; #pragma unroll
;           for (int kt = 0; kt < 4; ++kt)
; #pragma unroll
;             for (int j = 0; j < 4; ++j) {
;               const int kc = kt * 16 + fq * 4 + j;
;               const float okf = (rowok && (kc >= cst) && (kc < cst + 16)) ? 1.f : 0.f;
;               const float pv = __builtin_amdgcn_exp2f(__builtin_fmaf(s[kt][qt][j], c1, bv[kt][j] - m0)) * okf;
;               s[kt][qt][j] = pv; sum += pv;
;             }
.LBB0_1069:
	s_andn2_b64 vcc, exec, s[26:27]
	s_cbranch_vccnz .LBB0_1071
	v_subrev_u32_e32 v0, 31, v208
	s_movk_i32 s101, 0x740
	v_lshlrev_b32_e32 v211, 2, v0
	v_med3_i32 v2, v211, 0, s101
	ds_read_b32 v104, v2 offset:40960
	v_add_u32_e32 v2, 4, v211
	v_med3_i32 v2, v2, 0, s101
	ds_read_b32 v105, v2 offset:40960
	v_add_u32_e32 v2, 8, v211
	v_med3_i32 v2, v2, 0, s101
	ds_read_b32 v106, v2 offset:40960
	v_add_u32_e32 v2, 12, v211
	v_med3_i32 v2, v2, 0, s101
	ds_read_b32 v107, v2 offset:40960
	v_add_u32_e32 v2, 64, v211
	v_med3_i32 v2, v2, 0, s101
	ds_read_b32 v108, v2 offset:40960
	v_add_u32_e32 v2, 68, v211
	v_med3_i32 v2, v2, 0, s101
	ds_read_b32 v109, v2 offset:40960
	v_add_u32_e32 v2, 72, v211
	v_med3_i32 v2, v2, 0, s101
	ds_read_b32 v110, v2 offset:40960
	v_add_u32_e32 v2, 76, v211
	v_med3_i32 v2, v2, 0, s101
	ds_read_b32 v111, v2 offset:40960
	v_add_u32_e32 v2, 128, v211
	v_med3_i32 v2, v2, 0, s101
	ds_read_b32 v112, v2 offset:40960
	v_add_u32_e32 v2, 132, v211
	v_med3_i32 v2, v2, 0, s101
	ds_read_b32 v113, v2 offset:40960
	v_add_u32_e32 v2, 136, v211
	v_med3_i32 v2, v2, 0, s101
	ds_read_b32 v114, v2 offset:40960
	v_add_u32_e32 v2, 140, v211
	v_med3_i32 v2, v2, 0, s101
	ds_read_b32 v115, v2 offset:40960
	v_add_u32_e32 v2, 192, v211
	v_med3_i32 v2, v2, 0, s101
	ds_read_b32 v128, v2 offset:40960
	v_add_u32_e32 v2, 196, v211
	v_med3_i32 v2, v2, 0, s101
	s_add_i32 s26, s19, s43
	s_add_i32 s26, s26, -4
	ds_read_b32 v129, v2 offset:40960
	v_add_u32_e32 v2, 200, v211
	v_add_u32_e32 v0, 204, v211
	v_cmp_ge_i32_e32 vcc, s26, v164
	v_cmp_lt_i32_e64 s[40:41], s26, v163
	s_waitcnt lgkmcnt(13)
	v_med3_i32 v2, v2, 0, s101
	v_med3_i32 v0, v0, 0, s101
	s_or_b64 s[26:27], s[40:41], vcc
	v_fmac_f32_e32 v104, 0x3e38aa3b, v144
	s_waitcnt lgkmcnt(12)
	s_or_b64 s[40:41], s[26:27], s[58:59]
	v_exp_f32_e32 v130, v104
	v_fmac_f32_e32 v105, 0x3e38aa3b, v145
	ds_read_b32 v2, v2 offset:40960
	ds_read_b32 v3, v0 offset:40960
	v_cndmask_b32_e64 v0, 1.0, 0, s[40:41]
	v_readlane_b32 s40, v248, 21
	v_exp_f32_e32 v131, v105
	v_readlane_b32 s41, v248, 22
	s_or_b64 s[40:41], s[26:27], s[40:41]
	s_waitcnt lgkmcnt(13)
	v_mul_f32_e32 v104, v0, v130
	v_fma_f32 v0, v0, v130, 0
	v_cndmask_b32_e64 v130, 1.0, 0, s[40:41]
	v_fmac_f32_e32 v106, 0x3e38aa3b, v146
	v_mul_f32_e32 v105, v130, v131
	v_fmac_f32_e32 v0, v130, v131
	v_exp_f32_e32 v131, v106
	s_or_b64 s[40:41], s[26:27], s[52:53]
	s_waitcnt lgkmcnt(12)
	v_cndmask_b32_e64 v130, 1.0, 0, s[40:41]
	v_fmac_f32_e32 v107, 0x3e38aa3b, v147
	v_mul_f32_e32 v106, v130, v131
	v_fmac_f32_e32 v0, v130, v131
	v_exp_f32_e32 v131, v107
	s_or_b64 s[40:41], s[26:27], s[54:55]
	s_waitcnt lgkmcnt(11)
	v_cndmask_b32_e64 v130, 1.0, 0, s[40:41]
	v_fmac_f32_e32 v108, 0x3e38aa3b, v140
	v_mul_f32_e32 v107, v130, v131
	v_fmac_f32_e32 v0, v130, v131
	v_exp_f32_e32 v131, v108
	s_or_b64 s[40:41], s[26:27], s[56:57]
	s_waitcnt lgkmcnt(10)
	v_cndmask_b32_e64 v130, v165, 0, s[40:41]
	v_fmac_f32_e32 v109, 0x3e38aa3b, v141
	v_mul_f32_e32 v108, v130, v131
	v_fmac_f32_e32 v0, v130, v131
	v_exp_f32_e32 v131, v109
	s_or_b64 s[40:41], s[26:27], s[60:61]
	s_waitcnt lgkmcnt(9)
	v_cndmask_b32_e64 v130, v166, 0, s[40:41]
	v_fmac_f32_e32 v110, 0x3e38aa3b, v142
	v_mul_f32_e32 v109, v130, v131
	v_fmac_f32_e32 v0, v130, v131
	v_exp_f32_e32 v131, v110
	s_or_b64 s[40:41], s[26:27], s[50:51]
	s_waitcnt lgkmcnt(8)
	v_cndmask_b32_e64 v130, v168, 0, s[40:41]
	v_fmac_f32_e32 v111, 0x3e38aa3b, v143
	v_mul_f32_e32 v110, v130, v131
	v_fmac_f32_e32 v0, v130, v131
	v_exp_f32_e32 v131, v111
	s_or_b64 s[40:41], s[26:27], s[64:65]
	s_waitcnt lgkmcnt(7)
	v_cndmask_b32_e64 v130, v169, 0, s[40:41]
	v_fmac_f32_e32 v112, 0x3e38aa3b, v136
	v_mul_f32_e32 v111, v130, v131
	v_fmac_f32_e32 v0, v130, v131
	v_exp_f32_e32 v131, v112
	s_or_b64 s[40:41], s[26:27], s[66:67]
	s_waitcnt lgkmcnt(6)
	v_cndmask_b32_e64 v130, v170, 0, s[40:41]
	v_fmac_f32_e32 v113, 0x3e38aa3b, v137
	v_mul_f32_e32 v112, v130, v131
	v_fmac_f32_e32 v0, v130, v131
	v_exp_f32_e32 v131, v113
	s_or_b64 s[40:41], s[26:27], s[68:69]
	s_waitcnt lgkmcnt(5)
	v_cndmask_b32_e64 v130, v171, 0, s[40:41]
	v_fmac_f32_e32 v114, 0x3e38aa3b, v138
	v_mul_f32_e32 v113, v130, v131
	v_fmac_f32_e32 v0, v130, v131
	v_exp_f32_e32 v131, v114
	s_or_b64 s[40:41], s[26:27], s[70:71]
	s_waitcnt lgkmcnt(4)
	v_cndmask_b32_e64 v130, v172, 0, s[40:41]
	v_fmac_f32_e32 v115, 0x3e38aa3b, v139
	v_mul_f32_e32 v114, v130, v131
	v_fmac_f32_e32 v0, v130, v131
	v_exp_f32_e32 v131, v115
	s_or_b64 s[40:41], s[26:27], s[72:73]
	s_waitcnt lgkmcnt(3)
	v_cndmask_b32_e64 v130, v173, 0, s[40:41]
	v_fmac_f32_e32 v128, 0x3e38aa3b, v132
	v_mul_f32_e32 v115, v130, v131
	v_fmac_f32_e32 v0, v130, v131
	v_exp_f32_e32 v131, v128
	s_waitcnt lgkmcnt(2)
	v_cndmask_b32_e64 v130, v174, 0, s[26:27]
	v_fmac_f32_e32 v129, 0x3e38aa3b, v133
	s_waitcnt lgkmcnt(1)
	v_mul_f32_e32 v128, v130, v131
	v_fmac_f32_e32 v0, v130, v131
	v_exp_f32_e32 v131, v129
	v_fmac_f32_e32 v2, 0x3e38aa3b, v134
	s_waitcnt lgkmcnt(0)
	v_exp_f32_e32 v2, v2
	v_fmac_f32_e32 v3, 0x3e38aa3b, v135
	v_exp_f32_e32 v3, v3
	v_cndmask_b32_e64 v130, v175, 0, s[26:27]
	v_mul_f32_e32 v129, v130, v131
	v_fmac_f32_e32 v0, v130, v131
	v_cndmask_b32_e64 v131, v176, 0, s[26:27]
	v_mul_f32_e32 v130, v131, v2
	v_fmac_f32_e32 v0, v131, v2
	v_cndmask_b32_e64 v2, v177, 0, s[26:27]
	v_mul_f32_e32 v131, v2, v3
	v_fmac_f32_e32 v0, v2, v3

; template <int DQK, bool NA, bool SMAX, int LDV> ...
;     ...
;         if (NA && it >= 4) {
;           const int kr = rs + (it - 4);
;           const int ql = w * 32 + qt * 16 + fr, qr = r0 + (ql >> 6), qc = ql & 63;
;           const int rst = min(max(qr - 4, 0), 24);
;           const bool rowok = (kr >= rst) && (kr < rst + 8);
;           const int cst = min(max(qc - 8, 0), 48);
;           const int base = (kr - qr + 7) * 31 + 15 - qc;
;           float bv[4][4];
; #pragma unroll
;           for (int kt = 0; kt < 4; ++kt)
; #pragma unroll
;             for (int j = 0; j < 4; ++j) bv[kt][j] = rpbl[min(max(base + kt * 16 + fq * 4 + j, 0), 464)];
; #pragma unroll
;           for (int kt = 0; kt < 4; ++kt)
; #pragma unroll
;             for (int j = 0; j < 4; ++j) {
;               const int kc = kt * 16 + fq * 4 + j;
;               const float okf = (rowok && (kc >= cst) && (kc < cst + 16)) ? 1.f : 0.f;
;               const float pv = __builtin_amdgcn_exp2f(__builtin_fmaf(s[kt][qt][j], c1, bv[kt][j] - m0)) * okf;
;               s[kt][qt][j] = pv; sum += pv;
;             }
.LBB0_1073:
	s_andn2_b64 vcc, exec, s[0:1]
	s_cbranch_vccnz .LBB0_1075
	v_subrev_u32_e32 v2, 47, v208
	s_movk_i32 s101, 0x740
	v_lshlrev_b32_e32 v211, 2, v2
	v_med3_i32 v3, v211, 0, s101
	ds_read_b32 v132, v3 offset:40960
	v_add_u32_e32 v3, 4, v211
	v_med3_i32 v3, v3, 0, s101
	ds_read_b32 v133, v3 offset:40960
	v_add_u32_e32 v3, 8, v211
	v_med3_i32 v3, v3, 0, s101
	ds_read_b32 v134, v3 offset:40960
	v_add_u32_e32 v3, 12, v211
	v_med3_i32 v3, v3, 0, s101
	ds_read_b32 v135, v3 offset:40960
	v_add_u32_e32 v3, 64, v211
	v_med3_i32 v3, v3, 0, s101
	ds_read_b32 v136, v3 offset:40960
	v_add_u32_e32 v3, 68, v211
	v_med3_i32 v3, v3, 0, s101
	ds_read_b32 v137, v3 offset:40960
	v_add_u32_e32 v3, 72, v211
	v_med3_i32 v3, v3, 0, s101
	ds_read_b32 v138, v3 offset:40960
	v_add_u32_e32 v3, 76, v211
	v_med3_i32 v3, v3, 0, s101
	ds_read_b32 v139, v3 offset:40960
	v_add_u32_e32 v3, 128, v211
	v_med3_i32 v3, v3, 0, s101
	ds_read_b32 v140, v3 offset:40960
	v_add_u32_e32 v3, 132, v211
	v_med3_i32 v3, v3, 0, s101
	ds_read_b32 v141, v3 offset:40960
	v_add_u32_e32 v3, 136, v211
	v_med3_i32 v3, v3, 0, s101
	ds_read_b32 v142, v3 offset:40960
	v_add_u32_e32 v3, 140, v211
	v_med3_i32 v3, v3, 0, s101
	ds_read_b32 v143, v3 offset:40960
	v_add_u32_e32 v3, 192, v211
	v_med3_i32 v3, v3, 0, s101
	ds_read_b32 v144, v3 offset:40960
	v_add_u32_e32 v3, 196, v211
	v_med3_i32 v3, v3, 0, s101
	s_add_i32 s0, s19, s43
	s_waitcnt lgkmcnt(12)
	s_add_i32 s26, s0, -4
	ds_read_b32 v145, v3 offset:40960
	v_add_u32_e32 v3, 200, v211
	v_add_u32_e32 v2, 204, v211
	v_fmac_f32_e32 v132, 0x3e38aa3b, v124
	s_waitcnt lgkmcnt(12)
	v_cmp_ge_i32_e64 s[0:1], s26, v164
	v_cmp_lt_i32_e32 vcc, s26, v163
	v_exp_f32_e32 v124, v132
	v_fmac_f32_e32 v133, 0x3e38aa3b, v125
	v_med3_i32 v3, v3, 0, s101
	v_med3_i32 v2, v2, 0, s101
	s_or_b64 s[0:1], vcc, s[0:1]
	v_exp_f32_e32 v125, v133
	s_or_b64 s[26:27], s[0:1], s[82:83]
	ds_read_b32 v3, v3 offset:40960
	ds_read_b32 v147, v2 offset:40960
	v_cndmask_b32_e64 v2, 1.0, 0, s[26:27]
	s_or_b64 s[26:27], s[0:1], s[74:75]
	v_mul_f32_e32 v132, v2, v124
	v_fma_f32 v2, v2, v124, 0
	v_cndmask_b32_e64 v124, 1.0, 0, s[26:27]
	v_mul_f32_e32 v133, v124, v125
	v_fmac_f32_e32 v2, v124, v125
	s_waitcnt lgkmcnt(13)
	v_fma_f32 v125, v126, s62, v134
	v_exp_f32_e32 v125, v125
	s_or_b64 s[26:27], s[0:1], s[76:77]
	v_cndmask_b32_e64 v124, 1.0, 0, s[26:27]
	s_or_b64 s[26:27], s[0:1], s[78:79]
	v_mul_f32_e32 v134, v124, v125
	v_fmac_f32_e32 v2, v124, v125
	s_waitcnt lgkmcnt(12)
	v_fma_f32 v125, v127, s62, v135
	v_exp_f32_e32 v125, v125
	v_cndmask_b32_e64 v124, 1.0, 0, s[26:27]
	s_or_b64 s[26:27], s[0:1], s[80:81]
	s_waitcnt lgkmcnt(1)
	v_mul_f32_e32 v135, v124, v125
	v_fmac_f32_e32 v2, v124, v125
	v_fma_f32 v125, v120, s62, v136
	v_exp_f32_e32 v120, v125
	v_cndmask_b32_e64 v124, v178, 0, s[26:27]
	s_or_b64 s[26:27], s[0:1], s[84:85]
	v_fmac_f32_e32 v3, 0x3e38aa3b, v102
	v_mul_f32_e32 v136, v124, v120
	v_fmac_f32_e32 v2, v124, v120
	v_fma_f32 v124, v121, s62, v137
	v_exp_f32_e32 v121, v124
	v_cndmask_b32_e64 v120, v179, 0, s[26:27]
	s_or_b64 s[26:27], s[0:1], s[86:87]
	v_exp_f32_e32 v3, v3
	v_mul_f32_e32 v137, v120, v121
	v_fmac_f32_e32 v2, v120, v121
	v_fma_f32 v121, v122, s62, v138
	v_exp_f32_e32 v121, v121
	v_cndmask_b32_e64 v120, v180, 0, s[26:27]
	s_or_b64 s[26:27], s[0:1], s[88:89]
	v_mul_f32_e32 v138, v120, v121
	v_fmac_f32_e32 v2, v120, v121
	v_fma_f32 v121, v123, s62, v139
	v_exp_f32_e32 v121, v121
	v_cndmask_b32_e64 v120, v181, 0, s[26:27]
	s_or_b64 s[26:27], s[0:1], s[90:91]
	v_mul_f32_e32 v139, v120, v121
	v_fmac_f32_e32 v2, v120, v121
	v_fma_f32 v121, v116, s62, v140
	v_exp_f32_e32 v116, v121
	v_cndmask_b32_e64 v120, v182, 0, s[26:27]
	s_or_b64 s[26:27], s[0:1], s[92:93]
	v_mul_f32_e32 v140, v120, v116
	v_fmac_f32_e32 v2, v120, v116
	v_fma_f32 v120, v117, s62, v141
	v_exp_f32_e32 v117, v120
	v_cndmask_b32_e64 v116, v183, 0, s[26:27]
	s_or_b64 s[26:27], s[0:1], s[94:95]
	v_mul_f32_e32 v141, v116, v117
	v_fmac_f32_e32 v2, v116, v117
	v_fma_f32 v117, v118, s62, v142
	v_exp_f32_e32 v117, v117
	v_cndmask_b32_e64 v116, v184, 0, s[26:27]
	s_or_b64 s[26:27], s[0:1], s[96:97]
	v_mul_f32_e32 v142, v116, v117
	v_fmac_f32_e32 v2, v116, v117
	v_fma_f32 v117, v119, s62, v143
	v_exp_f32_e32 v117, v117
	v_cndmask_b32_e64 v116, v185, 0, s[26:27]
	v_mul_f32_e32 v143, v116, v117
	v_fmac_f32_e32 v2, v116, v117
	v_fma_f32 v117, v100, s62, v144
	v_exp_f32_e32 v100, v117
	v_cndmask_b32_e64 v116, v186, 0, s[0:1]
	v_mul_f32_e32 v144, v116, v100
	v_fmac_f32_e32 v2, v116, v100
	v_fma_f32 v116, v101, s62, v145
	v_exp_f32_e32 v101, v116
	v_cndmask_b32_e64 v100, v187, 0, s[0:1]
	v_mul_f32_e32 v145, v100, v101
	v_fmac_f32_e32 v2, v100, v101
	v_cndmask_b32_e64 v100, v189, 0, s[0:1]
	v_mul_f32_e32 v146, v100, v3
	v_fmac_f32_e32 v2, v100, v3
	s_waitcnt lgkmcnt(0)
	v_fma_f32 v100, v103, s62, v147
	v_exp_f32_e32 v100, v100
	v_cndmask_b32_e64 v3, v203, 0, s[0:1]
	v_mul_f32_e32 v147, v3, v100
	v_fmac_f32_e32 v2, v3, v100

; template <int DQK, bool NA, bool SMAX, int LDV> ...
;     ...
;         if (NA && it >= 4) {
;           const int kr = rs + (it - 4);
;           const int ql = w * 32 + qt * 16 + fr, qr = r0 + (ql >> 6), qc = ql & 63;
;           const int rst = min(max(qr - 4, 0), 24);
;           const bool rowok = (kr >= rst) && (kr < rst + 8);
;           const int cst = min(max(qc - 8, 0), 48);
;           const int base = (kr - qr + 7) * 31 + 15 - qc;
;           float bv[4][4];
; #pragma unroll
;           for (int kt = 0; kt < 4; ++kt)
; #pragma unroll
;             for (int j = 0; j < 4; ++j) bv[kt][j] = rpbl[min(max(base + kt * 16 + fq * 4 + j, 0), 464)];
; #pragma unroll
;           for (int kt = 0; kt < 4; ++kt)
; #pragma unroll
;             for (int j = 0; j < 4; ++j) {
;               const int kc = kt * 16 + fq * 4 + j;
;               const float okf = (rowok && (kc >= cst) && (kc < cst + 16)) ? 1.f : 0.f;
;               const float pv = __builtin_amdgcn_exp2f(__builtin_fmaf(s[kt][qt][j], c1, bv[kt][j] - m0)) * okf;
;               s[kt][qt][j] = pv; sum += pv;
;             }
.LBB0_1085:
	s_movk_i32 s101, 0x740
	v_lshlrev_b32_e32 v211, 2, v208
	v_add_u32_e32 v2, 4, v211
	v_add_u32_e32 v3, 204, v211
	v_med3_i32 v0, v211, 0, s101
	v_med3_i32 v2, v2, 0, s101
	v_med3_i32 v3, v3, 0, s101
	ds_read_b32 v0, v0 offset:40960
	ds_read_b32 v105, v2 offset:40960
	ds_read_b32 v3, v3 offset:40960
	v_add_u32_e32 v2, 8, v211
	v_med3_i32 v2, v2, 0, s101
	ds_read_b32 v106, v2 offset:40960
	v_add_u32_e32 v2, 12, v211
	s_add_i32 s0, s19, s43
	s_add_i32 s0, s0, -3
	v_med3_i32 v2, v2, 0, s101
	v_cmp_ge_i32_e32 vcc, s0, v164
	v_cmp_lt_i32_e64 s[0:1], s0, v163
	s_waitcnt lgkmcnt(3)
	ds_read_b32 v107, v2 offset:40960
	v_add_u32_e32 v2, 64, v211
	s_or_b64 s[0:1], s[0:1], vcc
	v_fmac_f32_e32 v0, 0x3e38aa3b, v144
	s_waitcnt lgkmcnt(3)
	s_or_b64 s[26:27], s[0:1], s[58:59]
	v_exp_f32_e32 v0, v0
	v_fmac_f32_e32 v105, 0x3e38aa3b, v145
	v_med3_i32 v2, v2, 0, s101
	v_cndmask_b32_e64 v130, 1.0, 0, s[26:27]
	v_readlane_b32 s26, v248, 21
	v_exp_f32_e32 v131, v105
	v_readlane_b32 s27, v248, 22
	ds_read_b32 v108, v2 offset:40960
	v_add_u32_e32 v2, 68, v211
	s_or_b64 s[26:27], s[0:1], s[26:27]
	s_waitcnt lgkmcnt(2)
	v_mul_f32_e32 v104, v130, v0
	v_fma_f32 v0, v130, v0, 0
	v_cndmask_b32_e64 v130, 1.0, 0, s[26:27]
	v_fmac_f32_e32 v106, 0x3e38aa3b, v146
	v_med3_i32 v2, v2, 0, s101
	v_mul_f32_e32 v105, v130, v131
	v_fmac_f32_e32 v0, v130, v131
	v_exp_f32_e32 v131, v106
	ds_read_b32 v109, v2 offset:40960
	v_add_u32_e32 v2, 72, v211
	s_or_b64 s[26:27], s[0:1], s[52:53]
	s_waitcnt lgkmcnt(2)
	v_cndmask_b32_e64 v130, 1.0, 0, s[26:27]
	v_fmac_f32_e32 v107, 0x3e38aa3b, v147
	v_med3_i32 v2, v2, 0, s101
	v_mul_f32_e32 v106, v130, v131
	v_fmac_f32_e32 v0, v130, v131
	v_exp_f32_e32 v131, v107
	ds_read_b32 v110, v2 offset:40960
	v_add_u32_e32 v2, 76, v211
	s_or_b64 s[26:27], s[0:1], s[54:55]
	s_waitcnt lgkmcnt(2)
	v_cndmask_b32_e64 v130, 1.0, 0, s[26:27]
	v_fmac_f32_e32 v108, 0x3e38aa3b, v140
	v_med3_i32 v2, v2, 0, s101
	v_mul_f32_e32 v107, v130, v131
	v_fmac_f32_e32 v0, v130, v131
	v_exp_f32_e32 v131, v108
	ds_read_b32 v111, v2 offset:40960
	v_add_u32_e32 v2, 128, v211
	s_or_b64 s[26:27], s[0:1], s[56:57]
	s_waitcnt lgkmcnt(2)
	v_cndmask_b32_e64 v130, v165, 0, s[26:27]
	v_fmac_f32_e32 v109, 0x3e38aa3b, v141
	v_med3_i32 v2, v2, 0, s101
	v_mul_f32_e32 v108, v130, v131
	v_fmac_f32_e32 v0, v130, v131
	v_exp_f32_e32 v131, v109
	ds_read_b32 v112, v2 offset:40960
	v_add_u32_e32 v2, 132, v211
	s_or_b64 s[26:27], s[0:1], s[60:61]
	s_waitcnt lgkmcnt(2)
	v_cndmask_b32_e64 v130, v166, 0, s[26:27]
	v_fmac_f32_e32 v110, 0x3e38aa3b, v142
	v_med3_i32 v2, v2, 0, s101
	v_mul_f32_e32 v109, v130, v131
	v_fmac_f32_e32 v0, v130, v131
	v_exp_f32_e32 v131, v110
	ds_read_b32 v113, v2 offset:40960
	v_add_u32_e32 v2, 136, v211
	s_or_b64 s[26:27], s[0:1], s[50:51]
	s_waitcnt lgkmcnt(2)
	v_cndmask_b32_e64 v130, v168, 0, s[26:27]
	v_fmac_f32_e32 v111, 0x3e38aa3b, v143
	v_med3_i32 v2, v2, 0, s101
	v_mul_f32_e32 v110, v130, v131
	v_fmac_f32_e32 v0, v130, v131
	v_exp_f32_e32 v131, v111
	ds_read_b32 v114, v2 offset:40960
	v_add_u32_e32 v2, 140, v211
	s_or_b64 s[26:27], s[0:1], s[64:65]
	s_waitcnt lgkmcnt(2)
	v_cndmask_b32_e64 v130, v169, 0, s[26:27]
	v_fmac_f32_e32 v112, 0x3e38aa3b, v136
	v_med3_i32 v2, v2, 0, s101
	v_mul_f32_e32 v111, v130, v131
	v_fmac_f32_e32 v0, v130, v131
	v_exp_f32_e32 v131, v112
	ds_read_b32 v115, v2 offset:40960
	v_add_u32_e32 v2, 192, v211
	s_or_b64 s[26:27], s[0:1], s[66:67]
	s_waitcnt lgkmcnt(2)
	v_cndmask_b32_e64 v130, v170, 0, s[26:27]
	v_fmac_f32_e32 v113, 0x3e38aa3b, v137
	v_med3_i32 v2, v2, 0, s101
	v_mul_f32_e32 v112, v130, v131
	v_fmac_f32_e32 v0, v130, v131
	v_exp_f32_e32 v131, v113
	ds_read_b32 v128, v2 offset:40960
	v_add_u32_e32 v2, 196, v211
	s_or_b64 s[26:27], s[0:1], s[68:69]
	s_waitcnt lgkmcnt(2)
	v_cndmask_b32_e64 v130, v171, 0, s[26:27]
	v_fmac_f32_e32 v114, 0x3e38aa3b, v138
	v_med3_i32 v2, v2, 0, s101
	v_mul_f32_e32 v113, v130, v131
	v_fmac_f32_e32 v0, v130, v131
	v_exp_f32_e32 v131, v114
	ds_read_b32 v129, v2 offset:40960
	v_add_u32_e32 v2, 200, v211
	s_or_b64 s[26:27], s[0:1], s[70:71]
	s_waitcnt lgkmcnt(2)
	v_cndmask_b32_e64 v130, v172, 0, s[26:27]
	v_fmac_f32_e32 v115, 0x3e38aa3b, v139
	v_med3_i32 v2, v2, 0, s101
	v_mul_f32_e32 v114, v130, v131
	v_fmac_f32_e32 v0, v130, v131
	v_exp_f32_e32 v131, v115
	ds_read_b32 v2, v2 offset:40960
	s_or_b64 s[26:27], s[0:1], s[72:73]
	s_waitcnt lgkmcnt(2)
	v_cndmask_b32_e64 v130, v173, 0, s[26:27]
	v_fmac_f32_e32 v128, 0x3e38aa3b, v132
	v_mul_f32_e32 v115, v130, v131
	v_fmac_f32_e32 v0, v130, v131
	v_exp_f32_e32 v131, v128
	s_waitcnt lgkmcnt(1)
	v_cndmask_b32_e64 v130, v174, 0, s[0:1]
	v_fmac_f32_e32 v129, 0x3e38aa3b, v133
	s_waitcnt lgkmcnt(0)
	v_mul_f32_e32 v128, v130, v131
	v_fmac_f32_e32 v0, v130, v131
	v_exp_f32_e32 v131, v129
	v_fmac_f32_e32 v2, 0x3e38aa3b, v134
	v_exp_f32_e32 v2, v2
	v_fmac_f32_e32 v3, 0x3e38aa3b, v135
	v_exp_f32_e32 v3, v3
	v_cndmask_b32_e64 v130, v175, 0, s[0:1]
	v_mul_f32_e32 v129, v130, v131
	v_fmac_f32_e32 v0, v130, v131
	v_cndmask_b32_e64 v131, v176, 0, s[0:1]
	v_mul_f32_e32 v130, v131, v2
	v_fmac_f32_e32 v0, v131, v2
	v_cndmask_b32_e64 v2, v177, 0, s[0:1]
	v_mul_f32_e32 v131, v2, v3
	v_fmac_f32_e32 v0, v2, v3

; template <int DQK, bool NA, bool SMAX, int LDV> ...
;     ...
;         if (NA && it >= 4) {
;           const int kr = rs + (it - 4);
;           const int ql = w * 32 + qt * 16 + fr, qr = r0 + (ql >> 6), qc = ql & 63;
;           const int rst = min(max(qr - 4, 0), 24);
;           const bool rowok = (kr >= rst) && (kr < rst + 8);
;           const int cst = min(max(qc - 8, 0), 48);
;           const int base = (kr - qr + 7) * 31 + 15 - qc;
;           float bv[4][4];
; #pragma unroll
;           for (int kt = 0; kt < 4; ++kt)
; #pragma unroll
;             for (int j = 0; j < 4; ++j) bv[kt][j] = rpbl[min(max(base + kt * 16 + fq * 4 + j, 0), 464)];
; #pragma unroll
;           for (int kt = 0; kt < 4; ++kt)
; #pragma unroll
;             for (int j = 0; j < 4; ++j) {
;               const int kc = kt * 16 + fq * 4 + j;
;               const float okf = (rowok && (kc >= cst) && (kc < cst + 16)) ? 1.f : 0.f;
;               const float pv = __builtin_amdgcn_exp2f(__builtin_fmaf(s[kt][qt][j], c1, bv[kt][j] - m0)) * okf;
;               s[kt][qt][j] = pv; sum += pv;
.LBB0_1089:
	v_add_u32_e32 v2, -16, v208
	s_movk_i32 s101, 0x740
	v_lshlrev_b32_e32 v211, 2, v2
	v_med3_i32 v3, v211, 0, s101
	ds_read_b32 v132, v3 offset:40960
	v_add_u32_e32 v3, 4, v211
	v_med3_i32 v3, v3, 0, s101
	ds_read_b32 v133, v3 offset:40960
	v_add_u32_e32 v3, 8, v211
	v_med3_i32 v3, v3, 0, s101
	ds_read_b32 v134, v3 offset:40960
	v_add_u32_e32 v3, 12, v211
	v_med3_i32 v3, v3, 0, s101
	ds_read_b32 v135, v3 offset:40960
	v_add_u32_e32 v3, 64, v211
	v_med3_i32 v3, v3, 0, s101
	ds_read_b32 v136, v3 offset:40960
	v_add_u32_e32 v3, 68, v211
	v_med3_i32 v3, v3, 0, s101
	ds_read_b32 v137, v3 offset:40960
	v_add_u32_e32 v3, 72, v211
	v_med3_i32 v3, v3, 0, s101
	ds_read_b32 v138, v3 offset:40960
	v_add_u32_e32 v3, 76, v211
	v_med3_i32 v3, v3, 0, s101
	ds_read_b32 v139, v3 offset:40960
	v_add_u32_e32 v3, 128, v211
	v_med3_i32 v3, v3, 0, s101
	ds_read_b32 v140, v3 offset:40960
	v_add_u32_e32 v3, 132, v211
	v_med3_i32 v3, v3, 0, s101
	ds_read_b32 v141, v3 offset:40960
	v_add_u32_e32 v3, 136, v211
	v_med3_i32 v3, v3, 0, s101
	ds_read_b32 v142, v3 offset:40960
	v_add_u32_e32 v3, 140, v211
	v_med3_i32 v3, v3, 0, s101
	ds_read_b32 v143, v3 offset:40960
	v_add_u32_e32 v3, 192, v211
	v_med3_i32 v3, v3, 0, s101
	ds_read_b32 v144, v3 offset:40960
	v_add_u32_e32 v3, 196, v211
	v_med3_i32 v3, v3, 0, s101
	s_add_i32 s0, s19, s43
	s_waitcnt lgkmcnt(12)
	s_add_i32 s0, s0, -3
	ds_read_b32 v145, v3 offset:40960
	v_add_u32_e32 v3, 200, v211
	v_add_u32_e32 v2, 204, v211
	v_fmac_f32_e32 v132, 0x3e38aa3b, v124
	s_waitcnt lgkmcnt(12)
	v_cmp_ge_i32_e32 vcc, s0, v164
	v_cmp_lt_i32_e64 s[0:1], s0, v163
	v_exp_f32_e32 v124, v132
	v_fmac_f32_e32 v133, 0x3e38aa3b, v125
	v_med3_i32 v3, v3, 0, s101
	v_med3_i32 v2, v2, 0, s101
	s_or_b64 s[0:1], s[0:1], vcc
	v_exp_f32_e32 v125, v133
	s_or_b64 s[26:27], s[0:1], s[82:83]
	ds_read_b32 v3, v3 offset:40960
	ds_read_b32 v147, v2 offset:40960
	v_cndmask_b32_e64 v2, 1.0, 0, s[26:27]
	s_or_b64 s[26:27], s[0:1], s[74:75]
	v_mul_f32_e32 v132, v2, v124
	v_fma_f32 v2, v2, v124, 0
	v_cndmask_b32_e64 v124, 1.0, 0, s[26:27]
	v_mul_f32_e32 v133, v124, v125
	v_fmac_f32_e32 v2, v124, v125
	s_waitcnt lgkmcnt(13)
	v_fma_f32 v125, v126, s62, v134
	v_exp_f32_e32 v125, v125
	s_or_b64 s[26:27], s[0:1], s[76:77]
	v_cndmask_b32_e64 v124, 1.0, 0, s[26:27]
	s_or_b64 s[26:27], s[0:1], s[78:79]
	v_mul_f32_e32 v134, v124, v125
	v_fmac_f32_e32 v2, v124, v125
	s_waitcnt lgkmcnt(12)
	v_fma_f32 v125, v127, s62, v135
	v_exp_f32_e32 v125, v125
	v_cndmask_b32_e64 v124, 1.0, 0, s[26:27]
	s_or_b64 s[26:27], s[0:1], s[80:81]
	s_waitcnt lgkmcnt(1)
	v_mul_f32_e32 v135, v124, v125
	v_fmac_f32_e32 v2, v124, v125
	v_fma_f32 v125, v120, s62, v136
	v_exp_f32_e32 v120, v125
	v_cndmask_b32_e64 v124, v178, 0, s[26:27]
	s_or_b64 s[26:27], s[0:1], s[84:85]
	v_fmac_f32_e32 v3, 0x3e38aa3b, v102
	v_mul_f32_e32 v136, v124, v120
	v_fmac_f32_e32 v2, v124, v120
	v_fma_f32 v124, v121, s62, v137
	v_exp_f32_e32 v121, v124
	v_cndmask_b32_e64 v120, v179, 0, s[26:27]
	s_or_b64 s[26:27], s[0:1], s[86:87]
	v_exp_f32_e32 v3, v3
	v_mul_f32_e32 v137, v120, v121
	v_fmac_f32_e32 v2, v120, v121
	v_fma_f32 v121, v122, s62, v138
	v_exp_f32_e32 v121, v121
	v_cndmask_b32_e64 v120, v180, 0, s[26:27]
	s_or_b64 s[26:27], s[0:1], s[88:89]
	v_mul_f32_e32 v138, v120, v121
	v_fmac_f32_e32 v2, v120, v121
	v_fma_f32 v121, v123, s62, v139
	v_exp_f32_e32 v121, v121
	v_cndmask_b32_e64 v120, v181, 0, s[26:27]
	s_or_b64 s[26:27], s[0:1], s[90:91]
	v_mul_f32_e32 v139, v120, v121
	v_fmac_f32_e32 v2, v120, v121
	v_fma_f32 v121, v116, s62, v140
	v_exp_f32_e32 v116, v121
	v_cndmask_b32_e64 v120, v182, 0, s[26:27]
	s_or_b64 s[26:27], s[0:1], s[92:93]
	v_mul_f32_e32 v140, v120, v116
	v_fmac_f32_e32 v2, v120, v116
	v_fma_f32 v120, v117, s62, v141
	v_exp_f32_e32 v117, v120
	v_cndmask_b32_e64 v116, v183, 0, s[26:27]
	s_or_b64 s[26:27], s[0:1], s[94:95]
	v_mul_f32_e32 v141, v116, v117
	v_fmac_f32_e32 v2, v116, v117
	v_fma_f32 v117, v118, s62, v142
	v_exp_f32_e32 v117, v117
	v_cndmask_b32_e64 v116, v184, 0, s[26:27]
	s_or_b64 s[26:27], s[0:1], s[96:97]
	v_mul_f32_e32 v142, v116, v117
	v_fmac_f32_e32 v2, v116, v117
	v_fma_f32 v117, v119, s62, v143
	v_exp_f32_e32 v117, v117
	v_cndmask_b32_e64 v116, v185, 0, s[26:27]
	v_mul_f32_e32 v143, v116, v117
	v_fmac_f32_e32 v2, v116, v117
	v_fma_f32 v117, v100, s62, v144
	v_exp_f32_e32 v100, v117
	v_cndmask_b32_e64 v116, v186, 0, s[0:1]
	v_mul_f32_e32 v144, v116, v100
	v_fmac_f32_e32 v2, v116, v100
	v_fma_f32 v116, v101, s62, v145
	v_exp_f32_e32 v101, v116
	v_cndmask_b32_e64 v100, v187, 0, s[0:1]
	v_mul_f32_e32 v145, v100, v101
	v_fmac_f32_e32 v2, v100, v101
	v_cndmask_b32_e64 v100, v189, 0, s[0:1]
	v_mul_f32_e32 v146, v100, v3
	v_fmac_f32_e32 v2, v100, v3
	s_waitcnt lgkmcnt(0)
	v_fma_f32 v100, v103, s62, v147
	v_exp_f32_e32 v100, v100
	v_cndmask_b32_e64 v3, v203, 0, s[0:1]
	v_mul_f32_e32 v147, v3, v100
	v_fmac_f32_e32 v2, v3, v100
